# final FFN-out epilogue: single vmcnt(0) after the 16 residual loads replaced by a counted-wait ladder (loads are consumed in issue order; stores counted as younger ops)
# baseline (speedup 1.0000x reference)
.LBB0_1276:
	v_mov_b32_e32 v128, v194
	v_mov_b32_e32 v129, v195
	s_lshl_b32 s16, s43, 8
	s_add_i32 s16, s16, s31
	v_add_u32_e32 v128, s16, v128
	s_lshl_b32 s16, s42, 8
	s_or_b32 s16, s16, s34
	v_lshl_add_u32 v130, v129, 3, s16
	v_ashrrev_i32_e32 v131, 31, v130
	v_ashrrev_i32_e32 v129, 31, v128
	v_lshl_add_u64 v[132:133], v[130:131], 1, s[58:59]
	v_lshlrev_b64 v[134:135], 11, v[128:129]
	v_add_u32_e32 v228, 16, v128
	v_lshl_add_u64 v[134:135], v[132:133], 0, v[134:135]
	v_ashrrev_i32_e32 v229, 31, v228
	global_load_dwordx4 v[200:203], v[134:135], off
	global_load_dwordx4 v[204:207], v[134:135], off offset:256
	v_lshlrev_b64 v[134:135], 11, v[228:229]
	v_lshl_add_u64 v[134:135], v[132:133], 0, v[134:135]
	global_load_dwordx4 v[208:211], v[134:135], off
	v_add_u32_e32 v192, 32, v128
	v_ashrrev_i32_e32 v193, 31, v192
	global_load_dwordx4 v[212:215], v[134:135], off offset:256
	v_lshlrev_b64 v[182:183], 2, v[130:131]
	v_lshlrev_b64 v[130:131], 11, v[192:193]
	v_lshl_add_u64 v[130:131], v[132:133], 0, v[130:131]
	global_load_dwordx4 v[216:219], v[130:131], off
	v_add_u32_e32 v190, 48, v128
	v_add_u32_e32 v188, 0x80, v128
	v_add_u32_e32 v186, 0x90, v128
	v_add_u32_e32 v184, 0xa0, v128
	v_add_u32_e32 v180, 0xb0, v128
	v_ashrrev_i32_e32 v191, 31, v190
	v_ashrrev_i32_e32 v189, 31, v188
	v_ashrrev_i32_e32 v187, 31, v186
	v_ashrrev_i32_e32 v185, 31, v184
	v_ashrrev_i32_e32 v181, 31, v180
	v_lshlrev_b64 v[128:129], 12, v[128:129]
	v_lshlrev_b64 v[134:135], 11, v[190:191]
	v_lshlrev_b64 v[136:137], 11, v[188:189]
	v_lshlrev_b64 v[138:139], 11, v[186:187]
	v_lshlrev_b64 v[140:141], 11, v[184:185]
	v_lshlrev_b64 v[142:143], 11, v[180:181]
	v_lshl_add_u64 v[128:129], s[6:7], 0, v[128:129]
	v_lshl_add_u64 v[134:135], v[132:133], 0, v[134:135]
	v_lshl_add_u64 v[136:137], v[132:133], 0, v[136:137]
	v_lshl_add_u64 v[138:139], v[132:133], 0, v[138:139]
	v_lshl_add_u64 v[230:231], v[132:133], 0, v[140:141]
	v_lshl_add_u64 v[232:233], v[132:133], 0, v[142:143]
	v_lshl_add_u64 v[234:235], v[128:129], 0, v[182:183]
	global_load_dwordx4 v[220:223], v[130:131], off offset:256
	global_load_dwordx4 v[224:227], v[134:135], off
	global_load_dwordx4 v[160:163], v[134:135], off offset:256
	global_load_dwordx4 v[156:159], v[136:137], off
	global_load_dwordx4 v[152:155], v[136:137], off offset:256
	global_load_dwordx4 v[148:151], v[138:139], off
	global_load_dwordx4 v[144:147], v[138:139], off offset:256
	global_load_dwordx4 v[140:143], v[230:231], off
	s_nop 0
	global_load_dwordx4 v[136:139], v[230:231], off offset:256
	global_load_dwordx4 v[132:135], v[232:233], off
	global_load_dwordx4 v[128:131], v[232:233], off offset:256
	s_and_b64 vcc, exec, s[0:1]
	s_mov_b64 s[0:1], -1
	s_waitcnt vmcnt(15)
	v_lshlrev_b32_e32 v230, 16, v200
	v_and_b32_e32 v231, 0xffff0000, v200
	v_lshlrev_b32_e32 v200, 16, v201
	v_and_b32_e32 v201, 0xffff0000, v201
	s_waitcnt vmcnt(14)
	v_lshlrev_b32_e32 v238, 16, v206
	v_and_b32_e32 v239, 0xffff0000, v206
	v_lshlrev_b32_e32 v232, 16, v202
	v_and_b32_e32 v233, 0xffff0000, v202
	v_lshlrev_b32_e32 v202, 16, v203
	v_and_b32_e32 v203, 0xffff0000, v203
	v_lshlrev_b32_e32 v236, 16, v204
	v_and_b32_e32 v237, 0xffff0000, v204
	v_lshlrev_b32_e32 v204, 16, v205
	v_and_b32_e32 v205, 0xffff0000, v205
	v_lshlrev_b32_e32 v206, 16, v207
	v_and_b32_e32 v207, 0xffff0000, v207
	v_pk_add_f32 v[126:127], v[126:127], v[200:201]
	v_pk_add_f32 v[124:125], v[124:125], v[230:231]
	v_pk_add_f32 v[108:109], v[108:109], v[238:239]
	v_pk_add_f32 v[122:123], v[122:123], v[202:203]
	v_pk_add_f32 v[120:121], v[120:121], v[232:233]
	v_pk_add_f32 v[118:119], v[118:119], v[204:205]
	v_pk_add_f32 v[116:117], v[116:117], v[236:237]
	v_pk_add_f32 v[110:111], v[110:111], v[206:207]
	global_store_dwordx4 v[234:235], v[124:127], off nt
	global_store_dwordx4 v[234:235], v[120:123], off offset:16 nt
	global_store_dwordx4 v[234:235], v[116:119], off offset:512 nt
	global_store_dwordx4 v[234:235], v[108:111], off offset:528 nt
	s_nop 0
	s_waitcnt vmcnt(17)
	v_lshlrev_b32_e32 v116, 16, v210
	v_lshlrev_b32_e32 v108, 16, v208
	v_and_b32_e32 v109, 0xffff0000, v208
	v_pk_add_f32 v[108:109], v[112:113], v[108:109]
	v_lshlrev_b64 v[112:113], 12, v[228:229]
	v_lshlrev_b32_e32 v110, 16, v209
	v_and_b32_e32 v111, 0xffff0000, v209
	v_and_b32_e32 v117, 0xffff0000, v210
	v_lshlrev_b32_e32 v118, 16, v211
	v_and_b32_e32 v119, 0xffff0000, v211
	v_lshl_add_u64 v[112:113], s[6:7], 0, v[112:113]
	v_pk_add_f32 v[110:111], v[114:115], v[110:111]
	v_pk_add_f32 v[106:107], v[106:107], v[118:119]
	v_pk_add_f32 v[104:105], v[104:105], v[116:117]
	v_lshl_add_u64 v[112:113], v[112:113], 0, v[182:183]
	global_store_dwordx4 v[112:113], v[108:111], off nt
	global_store_dwordx4 v[112:113], v[104:107], off offset:16 nt
	s_nop 0
	s_waitcnt vmcnt(18)
	v_lshlrev_b32_e32 v108, 16, v214
	v_lshlrev_b32_e32 v104, 16, v212
	v_and_b32_e32 v105, 0xffff0000, v212
	v_lshlrev_b32_e32 v106, 16, v213
	v_and_b32_e32 v107, 0xffff0000, v213
	v_and_b32_e32 v109, 0xffff0000, v214
	v_lshlrev_b32_e32 v110, 16, v215
	v_and_b32_e32 v111, 0xffff0000, v215
	v_pk_add_f32 v[102:103], v[102:103], v[106:107]
	v_pk_add_f32 v[100:101], v[100:101], v[104:105]
	v_pk_add_f32 v[92:93], v[92:93], v[108:109]
	v_pk_add_f32 v[94:95], v[94:95], v[110:111]
	global_store_dwordx4 v[112:113], v[100:103], off offset:512 nt
	global_store_dwordx4 v[112:113], v[92:95], off offset:528 nt
	s_nop 0
	s_waitcnt vmcnt(19)
	v_lshlrev_b32_e32 v100, 16, v218
	v_lshlrev_b32_e32 v92, 16, v216
	v_and_b32_e32 v93, 0xffff0000, v216
	v_pk_add_f32 v[92:93], v[96:97], v[92:93]
	v_lshlrev_b64 v[96:97], 12, v[192:193]
	v_lshlrev_b32_e32 v94, 16, v217
	v_and_b32_e32 v95, 0xffff0000, v217
	v_and_b32_e32 v101, 0xffff0000, v218
	v_lshlrev_b32_e32 v102, 16, v219
	v_and_b32_e32 v103, 0xffff0000, v219
	v_lshl_add_u64 v[96:97], s[6:7], 0, v[96:97]
	v_pk_add_f32 v[94:95], v[98:99], v[94:95]
	v_pk_add_f32 v[90:91], v[90:91], v[102:103]
	v_pk_add_f32 v[88:89], v[88:89], v[100:101]
	v_lshl_add_u64 v[96:97], v[96:97], 0, v[182:183]
	global_store_dwordx4 v[96:97], v[92:95], off nt
	global_store_dwordx4 v[96:97], v[88:91], off offset:16 nt
	s_nop 0
	s_waitcnt vmcnt(20)
	v_lshlrev_b32_e32 v92, 16, v222
	v_lshlrev_b32_e32 v88, 16, v220
	v_and_b32_e32 v89, 0xffff0000, v220
	v_lshlrev_b32_e32 v90, 16, v221
	v_and_b32_e32 v91, 0xffff0000, v221
	v_and_b32_e32 v93, 0xffff0000, v222
	v_lshlrev_b32_e32 v94, 16, v223
	v_and_b32_e32 v95, 0xffff0000, v223
	v_pk_add_f32 v[86:87], v[86:87], v[90:91]
	v_pk_add_f32 v[84:85], v[84:85], v[88:89]
	v_pk_add_f32 v[76:77], v[76:77], v[92:93]
	v_pk_add_f32 v[78:79], v[78:79], v[94:95]
	global_store_dwordx4 v[96:97], v[84:87], off offset:512 nt
	global_store_dwordx4 v[96:97], v[76:79], off offset:528 nt
	s_nop 0
	s_waitcnt vmcnt(21)
	v_lshlrev_b32_e32 v84, 16, v226
	v_lshlrev_b32_e32 v76, 16, v224
	v_and_b32_e32 v77, 0xffff0000, v224
	v_pk_add_f32 v[76:77], v[80:81], v[76:77]
	v_lshlrev_b64 v[80:81], 12, v[190:191]
	v_lshlrev_b32_e32 v78, 16, v225
	v_and_b32_e32 v79, 0xffff0000, v225
	v_and_b32_e32 v85, 0xffff0000, v226
	v_lshlrev_b32_e32 v86, 16, v227
	v_and_b32_e32 v87, 0xffff0000, v227
	v_lshl_add_u64 v[80:81], s[6:7], 0, v[80:81]
	v_pk_add_f32 v[78:79], v[82:83], v[78:79]
	v_pk_add_f32 v[74:75], v[74:75], v[86:87]
	v_pk_add_f32 v[72:73], v[72:73], v[84:85]
	v_lshl_add_u64 v[80:81], v[80:81], 0, v[182:183]
	global_store_dwordx4 v[80:81], v[76:79], off nt
	global_store_dwordx4 v[80:81], v[72:75], off offset:16 nt
	s_nop 0
	s_waitcnt vmcnt(22)
	v_lshlrev_b32_e32 v76, 16, v162
	v_lshlrev_b32_e32 v72, 16, v160
	v_and_b32_e32 v73, 0xffff0000, v160
	v_lshlrev_b32_e32 v74, 16, v161
	v_and_b32_e32 v75, 0xffff0000, v161
	v_and_b32_e32 v77, 0xffff0000, v162
	v_lshlrev_b32_e32 v78, 16, v163
	v_and_b32_e32 v79, 0xffff0000, v163
	v_pk_add_f32 v[70:71], v[70:71], v[74:75]
	v_pk_add_f32 v[68:69], v[68:69], v[72:73]
	v_pk_add_f32 v[64:65], v[64:65], v[76:77]
	v_pk_add_f32 v[66:67], v[66:67], v[78:79]
	global_store_dwordx4 v[80:81], v[68:71], off offset:512 nt
	global_store_dwordx4 v[80:81], v[64:67], off offset:528 nt
	s_nop 0
	s_waitcnt vmcnt(23)
	v_lshlrev_b32_e32 v68, 16, v158
	v_lshlrev_b32_e32 v64, 16, v156
	v_and_b32_e32 v65, 0xffff0000, v156
	v_pk_add_f32 v[60:61], v[60:61], v[64:65]
	v_lshlrev_b64 v[64:65], 12, v[188:189]
	v_lshlrev_b32_e32 v66, 16, v157
	v_and_b32_e32 v67, 0xffff0000, v157
	v_and_b32_e32 v69, 0xffff0000, v158
	v_lshlrev_b32_e32 v70, 16, v159
	v_and_b32_e32 v71, 0xffff0000, v159
	v_lshl_add_u64 v[64:65], s[6:7], 0, v[64:65]
	v_pk_add_f32 v[62:63], v[62:63], v[66:67]
	v_pk_add_f32 v[58:59], v[58:59], v[70:71]
	v_pk_add_f32 v[56:57], v[56:57], v[68:69]
	v_lshl_add_u64 v[64:65], v[64:65], 0, v[182:183]
	global_store_dwordx4 v[64:65], v[60:63], off nt
	global_store_dwordx4 v[64:65], v[56:59], off offset:16 nt
	s_nop 0
	s_waitcnt vmcnt(24)
	v_lshlrev_b32_e32 v60, 16, v154
	v_lshlrev_b32_e32 v56, 16, v152
	v_and_b32_e32 v57, 0xffff0000, v152
	v_lshlrev_b32_e32 v58, 16, v153
	v_and_b32_e32 v59, 0xffff0000, v153
	v_and_b32_e32 v61, 0xffff0000, v154
	v_lshlrev_b32_e32 v62, 16, v155
	v_and_b32_e32 v63, 0xffff0000, v155
	v_pk_add_f32 v[54:55], v[54:55], v[58:59]
	v_pk_add_f32 v[52:53], v[52:53], v[56:57]
	v_pk_add_f32 v[44:45], v[44:45], v[60:61]
	v_pk_add_f32 v[46:47], v[46:47], v[62:63]
	global_store_dwordx4 v[64:65], v[52:55], off offset:512 nt
	global_store_dwordx4 v[64:65], v[44:47], off offset:528 nt
	s_nop 0
	s_waitcnt vmcnt(25)
	v_lshlrev_b32_e32 v52, 16, v150
	v_lshlrev_b32_e32 v44, 16, v148
	v_and_b32_e32 v45, 0xffff0000, v148
	v_pk_add_f32 v[44:45], v[48:49], v[44:45]
	v_lshlrev_b64 v[48:49], 12, v[186:187]
	v_lshlrev_b32_e32 v46, 16, v149
	v_and_b32_e32 v47, 0xffff0000, v149
	v_and_b32_e32 v53, 0xffff0000, v150
	v_lshlrev_b32_e32 v54, 16, v151
	v_and_b32_e32 v55, 0xffff0000, v151
	v_lshl_add_u64 v[48:49], s[6:7], 0, v[48:49]
	v_pk_add_f32 v[46:47], v[50:51], v[46:47]
	v_pk_add_f32 v[42:43], v[42:43], v[54:55]
	v_pk_add_f32 v[40:41], v[40:41], v[52:53]
	v_lshl_add_u64 v[48:49], v[48:49], 0, v[182:183]
	global_store_dwordx4 v[48:49], v[44:47], off nt
	global_store_dwordx4 v[48:49], v[40:43], off offset:16 nt
	s_nop 0
	s_waitcnt vmcnt(26)
	v_lshlrev_b32_e32 v44, 16, v146
	v_lshlrev_b32_e32 v40, 16, v144
	v_and_b32_e32 v41, 0xffff0000, v144
	v_lshlrev_b32_e32 v42, 16, v145
	v_and_b32_e32 v43, 0xffff0000, v145
	v_and_b32_e32 v45, 0xffff0000, v146
	v_lshlrev_b32_e32 v46, 16, v147
	v_and_b32_e32 v47, 0xffff0000, v147
	v_pk_add_f32 v[38:39], v[38:39], v[42:43]
	v_pk_add_f32 v[36:37], v[36:37], v[40:41]
	v_pk_add_f32 v[28:29], v[28:29], v[44:45]
	v_pk_add_f32 v[30:31], v[30:31], v[46:47]
	global_store_dwordx4 v[48:49], v[36:39], off offset:512 nt
	global_store_dwordx4 v[48:49], v[28:31], off offset:528 nt
	s_nop 0
	s_waitcnt vmcnt(27)
	v_lshlrev_b32_e32 v36, 16, v142
	v_lshlrev_b32_e32 v28, 16, v140
	v_and_b32_e32 v29, 0xffff0000, v140
	v_pk_add_f32 v[28:29], v[32:33], v[28:29]
	v_lshlrev_b64 v[32:33], 12, v[184:185]
	v_lshlrev_b32_e32 v30, 16, v141
	v_and_b32_e32 v31, 0xffff0000, v141
	v_and_b32_e32 v37, 0xffff0000, v142
	v_lshlrev_b32_e32 v38, 16, v143
	v_and_b32_e32 v39, 0xffff0000, v143
	v_lshl_add_u64 v[32:33], s[6:7], 0, v[32:33]
	v_pk_add_f32 v[30:31], v[34:35], v[30:31]
	v_pk_add_f32 v[26:27], v[26:27], v[38:39]
	v_pk_add_f32 v[24:25], v[24:25], v[36:37]
	v_lshl_add_u64 v[32:33], v[32:33], 0, v[182:183]
	global_store_dwordx4 v[32:33], v[28:31], off nt
	global_store_dwordx4 v[32:33], v[24:27], off offset:16 nt
	s_nop 0
	s_waitcnt vmcnt(28)
	v_lshlrev_b32_e32 v28, 16, v138
	v_lshlrev_b32_e32 v24, 16, v136
	v_and_b32_e32 v25, 0xffff0000, v136
	v_lshlrev_b32_e32 v26, 16, v137
	v_and_b32_e32 v27, 0xffff0000, v137
	v_and_b32_e32 v29, 0xffff0000, v138
	v_lshlrev_b32_e32 v30, 16, v139
	v_and_b32_e32 v31, 0xffff0000, v139
	v_pk_add_f32 v[22:23], v[22:23], v[26:27]
	v_pk_add_f32 v[20:21], v[20:21], v[24:25]
	v_pk_add_f32 v[12:13], v[12:13], v[28:29]
	v_pk_add_f32 v[14:15], v[14:15], v[30:31]
	global_store_dwordx4 v[32:33], v[20:23], off offset:512 nt
	global_store_dwordx4 v[32:33], v[12:15], off offset:528 nt
	s_nop 0
	s_waitcnt vmcnt(29)
	v_lshlrev_b32_e32 v20, 16, v134
	v_lshlrev_b32_e32 v12, 16, v132
	v_and_b32_e32 v13, 0xffff0000, v132
	v_pk_add_f32 v[12:13], v[16:17], v[12:13]
	v_lshlrev_b64 v[16:17], 12, v[180:181]
	v_lshlrev_b32_e32 v14, 16, v133
	v_and_b32_e32 v15, 0xffff0000, v133
	v_and_b32_e32 v21, 0xffff0000, v134
	v_lshlrev_b32_e32 v22, 16, v135
	v_and_b32_e32 v23, 0xffff0000, v135
	v_lshl_add_u64 v[16:17], s[6:7], 0, v[16:17]
	v_pk_add_f32 v[14:15], v[18:19], v[14:15]
	v_pk_add_f32 v[10:11], v[10:11], v[22:23]
	v_pk_add_f32 v[8:9], v[8:9], v[20:21]
	v_lshl_add_u64 v[16:17], v[16:17], 0, v[182:183]
	global_store_dwordx4 v[16:17], v[12:15], off nt
	global_store_dwordx4 v[16:17], v[8:11], off offset:16 nt
	s_nop 0
	s_waitcnt vmcnt(30)
	v_lshlrev_b32_e32 v12, 16, v130
	v_lshlrev_b32_e32 v8, 16, v128
	v_and_b32_e32 v9, 0xffff0000, v128
	v_lshlrev_b32_e32 v10, 16, v129
	v_and_b32_e32 v11, 0xffff0000, v129
	v_and_b32_e32 v13, 0xffff0000, v130
	v_lshlrev_b32_e32 v14, 16, v131
	v_and_b32_e32 v15, 0xffff0000, v131
	v_pk_add_f32 v[6:7], v[6:7], v[10:11]
	v_pk_add_f32 v[4:5], v[4:5], v[8:9]
	v_pk_add_f32 v[2:3], v[2:3], v[14:15]
	v_pk_add_f32 v[0:1], v[0:1], v[12:13]
	global_store_dwordx4 v[16:17], v[4:7], off offset:512 nt
	global_store_dwordx4 v[16:17], v[0:3], off offset:528 nt
	s_cbranch_vccnz .LBB0_1261
	s_andn2_b64 vcc, exec, s[8:9]
	s_cbranch_vccnz .LBB0_1260
	s_barrier
	s_branch .LBB0_1260
